# kblocked_hbuf_and_wtin_no_stagger
# speedup vs baseline: 1.0802x; 1.0038x over previous
.Ltr_loop:
	s_sub_i32 s80, s74, 0x2040
	s_movk_i32 s86, 0x400
	s_mov_b32 s92, 0x10a40000
	s_cmpk_lt_u32 s80, 0x420
	s_cselect_b32 s84, s64, s46
	s_cselect_b32 s85, s65, s47
	s_cselect_b32 s86, 0x1010, s86
	s_cselect_b32 s92, 0x10200000, s92
	s_cselect_b64 s[88:89], -1, 0
	s_cselect_b32 s96, 6, 11
	s_movk_i32 s97, 0x40
	s_cselect_b32 s97, 0x42000, s97
	s_movk_i32 s98, 0x80
	s_cselect_b32 s98, 0x84000, s98
	s_cselect_b32 s81, 0, 0x420
	s_sub_u32 s80, s80, s81
	s_lshr_b32 s82, s80, 4
	s_and_b32 s83, s80, 15
	s_lshl_b32 s87, s86, 4
	s_add_u32 s92, s20, s92
	s_addc_u32 s93, s21, 0
	v_lshl_add_u32 v66, s82, 6, v64
	v_add_u32_e32 v67, 16, v66
	v_add_u32_e32 v68, 0xfffff800, v66
	v_cmp_gt_u32_e32 vcc, 0x800, v66
	s_nop 1
	v_cndmask_b32_e32 v69, v67, v66, vcc
	v_cmp_gt_u32_e32 vcc, 0x1000, v66
	s_nop 1
	v_cndmask_b32_e32 v69, v68, v69, vcc
	v_cmp_gt_u32_e64 s[90:91], s86, v66
	v_cndmask_b32_e64 v69, v66, v69, s[88:89]
	s_orn2_b64 s[90:91], s[90:91], s[88:89]
	v_lshl_add_u32 v70, s83, 6, v65
	v_mul_lo_u32 v70, v70, s86
	v_add_lshl_u32 v70, v70, v69, 2
	v_mov_b32_e32 v72, 0
	v_mov_b32_e32 v73, 0
	v_mov_b32_e32 v74, 0
	v_mov_b32_e32 v75, 0
	v_mov_b32_e32 v76, 0
	v_mov_b32_e32 v77, 0
	v_mov_b32_e32 v78, 0
	v_mov_b32_e32 v79, 0
	v_mov_b32_e32 v80, 0
	v_mov_b32_e32 v81, 0
	v_mov_b32_e32 v82, 0
	v_mov_b32_e32 v83, 0
	v_mov_b32_e32 v84, 0
	v_mov_b32_e32 v85, 0
	v_mov_b32_e32 v86, 0
	v_mov_b32_e32 v87, 0
	s_mov_b64 vcc, exec
	s_and_b64 exec, exec, s[90:91]
	global_load_dword v72, v70, s[84:85] nt
	v_add_u32_e32 v70, s87, v70
	global_load_dword v73, v70, s[84:85] nt
	v_add_u32_e32 v70, s87, v70
	global_load_dword v74, v70, s[84:85] nt
	v_add_u32_e32 v70, s87, v70
	global_load_dword v75, v70, s[84:85] nt
	v_add_u32_e32 v70, s87, v70
	global_load_dword v76, v70, s[84:85] nt
	v_add_u32_e32 v70, s87, v70
	global_load_dword v77, v70, s[84:85] nt
	v_add_u32_e32 v70, s87, v70
	global_load_dword v78, v70, s[84:85] nt
	v_add_u32_e32 v70, s87, v70
	global_load_dword v79, v70, s[84:85] nt
	v_add_u32_e32 v70, s87, v70
	global_load_dword v80, v70, s[84:85] nt
	v_add_u32_e32 v70, s87, v70
	global_load_dword v81, v70, s[84:85] nt
	v_add_u32_e32 v70, s87, v70
	global_load_dword v82, v70, s[84:85] nt
	v_add_u32_e32 v70, s87, v70
	global_load_dword v83, v70, s[84:85] nt
	v_add_u32_e32 v70, s87, v70
	global_load_dword v84, v70, s[84:85] nt
	v_add_u32_e32 v70, s87, v70
	global_load_dword v85, v70, s[84:85] nt
	v_add_u32_e32 v70, s87, v70
	global_load_dword v86, v70, s[84:85] nt
	v_add_u32_e32 v70, s87, v70
	global_load_dword v87, v70, s[84:85] nt
	s_mov_b64 exec, vcc
	s_barrier
	s_waitcnt vmcnt(0)
	ds_write_b32 v71, v72
	ds_write_b32 v71, v73 offset:1040
	ds_write_b32 v71, v74 offset:2080
	ds_write_b32 v71, v75 offset:3120
	ds_write_b32 v71, v76 offset:4160
	ds_write_b32 v71, v77 offset:5200
	ds_write_b32 v71, v78 offset:6240
	ds_write_b32 v71, v79 offset:7280
	ds_write_b32 v71, v80 offset:8320
	ds_write_b32 v71, v81 offset:9360
	ds_write_b32 v71, v82 offset:10400
	ds_write_b32 v71, v83 offset:11440
	ds_write_b32 v71, v84 offset:12480
	ds_write_b32 v71, v85 offset:13520
	ds_write_b32 v71, v86 offset:14560
	ds_write_b32 v71, v87 offset:15600
	s_waitcnt lgkmcnt(0)
	s_barrier
	ds_read_b32 v72, v90
	ds_read_b32 v73, v90 offset:260
	ds_read_b32 v74, v90 offset:520
	ds_read_b32 v75, v90 offset:780
	ds_read_b32 v76, v90 offset:1040
	ds_read_b32 v77, v90 offset:1300
	ds_read_b32 v78, v90 offset:1560
	ds_read_b32 v79, v90 offset:1820
	ds_read_b32 v80, v90 offset:8320
	ds_read_b32 v81, v90 offset:8580
	ds_read_b32 v82, v90 offset:8840
	ds_read_b32 v83, v90 offset:9100
	ds_read_b32 v84, v90 offset:9360
	ds_read_b32 v85, v90 offset:9620
	ds_read_b32 v86, v90 offset:9880
	ds_read_b32 v87, v90 offset:10140
	v_lshl_add_u32 v91, s82, 6, v88
	v_lshlrev_b32_e32 v91, s96, v91
	v_lshl_add_u32 v91, v89, 4, v91
	s_mul_i32 s81, s83, s98
	v_add_u32_e32 v91, s81, v91
	v_add_u32_e32 v100, s97, v91
	s_waitcnt lgkmcnt(0)
	v_cvt_pk_bf16_f32 v92, v72, v73
	v_cvt_pk_bf16_f32 v93, v74, v75
	v_cvt_pk_bf16_f32 v94, v76, v77
	v_cvt_pk_bf16_f32 v95, v78, v79
	v_cvt_pk_bf16_f32 v96, v80, v81
	v_cvt_pk_bf16_f32 v97, v82, v83
	v_cvt_pk_bf16_f32 v98, v84, v85
	v_cvt_pk_bf16_f32 v99, v86, v87
	global_store_dwordx4 v91, v[92:95], s[92:93]
	global_store_dwordx4 v100, v[96:99], s[92:93]
	s_add_i32 s74, s74, s22
	s_cmpk_lt_i32 s74, 0x2560
	s_cbranch_scc1 .Ltr_loop
	s_branch .LBB0_44
	s_branch .LBB0_18

.LBB0_95:
	s_or_b64 exec, exec, s[0:1]
	s_and_b32 s28, s2, 7
	s_xor_b32 s0, s28, 7
	s_add_i32 s0, s22, s0
	s_ashr_i32 s1, s0, 31
	s_lshr_b32 s1, s1, 29
	s_add_i32 s0, s0, s1
	s_lshr_b32 s88, s2, 3
	s_ashr_i32 s89, s0, 3
	s_cmp_lt_i32 s22, 8
	s_cselect_b64 s[0:1], -1, 0
	v_writelane_b32 v244, s0, 2
	s_barrier
	s_nop 0
	v_writelane_b32 v244, s1, 3
	s_and_b64 s[0:1], s[0:1], exec
	s_cselect_b32 s78, s2, s28
	s_cselect_b32 s29, 0, s88
	s_cmp_gt_i32 s78, 63
	s_cselect_b64 s[0:1], -1, 0
	s_cmp_gt_u32 s29, 63
	s_cselect_b64 s[4:5], -1, 0
	s_or_b64 s[0:1], s[0:1], s[4:5]
	s_and_b64 vcc, exec, s[0:1]
	s_cbranch_vccnz .LBB0_251
	v_readlane_b32 s0, v244, 2
	s_min_i32 s79, s22, 8
	v_readlane_b32 s1, v244, 3
	s_and_b64 s[0:1], s[0:1], exec
	s_cselect_b32 s80, 1, s89
	s_add_u32 s4, s20, 0x10200000
	s_addc_u32 s5, s21, 0
	s_mov_b64 s[0:1], 0
	v_mov_b32_e32 v129, 0
	s_mov_b64 s[6:7], 0x1000
	s_mov_b64 s[8:9], 0x2000
	s_mov_b64 s[10:11], 0x3000
	s_mov_b64 s[12:13], 0x204000
	s_mov_b64 s[14:15], 0x1000
	s_mov_b64 s[16:17], 0x42000
	s_mov_b64 s[34:35], 0x10242000
	s_mov_b64 s[46:47], 0x10243000
	s_movk_i32 s81, 0x80
	s_movk_i32 s82, 0x7fff
	s_movk_i32 s83, 0x1800
	s_mov_b64 s[62:63], 0x8292000
	s_movk_i32 s84, 0x1fff
	s_movk_i32 s85, 0x1ffc
	s_mov_b64 s[64:65], 0x8100000
	s_movk_i32 s86, 0x110
	v_mov_b32_e32 v140, 0x70
	s_mov_b32 s87, s29
	s_branch .LBB0_98

.LBB0_98:
	s_lshl_b32 s24, s78, 1
	s_and_b32 s24, s24, -8
	s_and_b32 s33, s87, 7
	s_or_b32 s69, s24, s33
	s_lshl_b32 s24, s78, 3
	s_and_b32 s72, s24, 24
	s_ashr_i32 s24, s87, 3
	s_add_i32 s72, s72, s24
	v_mov_b32_e32 v141, v181
	v_mov_b32_e32 v2, v181
	s_lshl_b32 s68, s72, 7
	s_lshl_b32 s90, s69, 8
	v_ashrrev_i32_e32 v142, 2, v2
	v_lshlrev_b32_e32 v3, 3, v2
	v_add_u32_e32 v0, s68, v142
	v_bitop3_b32 v4, v3, 24, v2 bitop3:0x48
	v_ashrrev_i32_e32 v1, 31, v0
	v_lshlrev_b32_e32 v144, 4, v2
	v_lshlrev_b64 v[0:1], 6, v[0:1]
	s_and_b64 vcc, exec, s[0:1]
	v_add_u32_e32 v143, 0x1000, v144
	v_add_u32_e32 v139, 0x2000, v144
	v_add_u32_e32 v138, 0x3000, v144
	v_add_u32_e32 v137, 0x4000, v144
	v_add_u32_e32 v136, 0x5000, v144
	v_lshlrev_b32_e32 v130, 1, v4
	s_cbranch_vccnz .LBB0_100
	v_add_u32_e32 v4, s90, v142
	v_ashrrev_i32_e32 v5, 31, v4
	v_lshlrev_b64 v[4:5], 6, v[4:5]
	v_lshl_add_u64 v[4:5], s[50:51], 0, v[4:5]
	v_mov_b32_e32 v131, v129
	v_readfirstlane_b32 s0, v144
	v_lshl_add_u64 v[4:5], v[4:5], 0, v[130:131]
	s_mov_b32 m0, s0
	v_readfirstlane_b32 s0, v143
	s_barrier
	global_load_lds_dwordx4 v[4:5], off
	v_lshl_add_u64 v[8:9], v[4:5], 0, s[14:15]
	s_mov_b32 m0, s0
	v_readfirstlane_b32 s0, v139
	global_load_lds_dwordx4 v[8:9], off
	v_lshl_add_u64 v[8:9], v[4:5], 0, s[8:9]
	s_mov_b32 m0, s0
	v_readfirstlane_b32 s0, v138
	v_lshl_add_u64 v[6:7], s[4:5], 0, v[0:1]
	global_load_lds_dwordx4 v[8:9], off
	v_lshl_add_u64 v[4:5], v[4:5], 0, s[10:11]
	s_mov_b32 m0, s0
	v_readfirstlane_b32 s0, v137
	v_lshl_add_u64 v[6:7], v[6:7], 0, v[130:131]
	global_load_lds_dwordx4 v[4:5], off
	s_mov_b32 m0, s0
	v_readfirstlane_b32 s0, v136
	global_load_lds_dwordx4 v[6:7], off
	v_lshl_add_u64 v[4:5], v[6:7], 0, s[6:7]
	s_mov_b32 m0, s0
	s_nop 0
	global_load_lds_dwordx4 v[4:5], off
.LBB0_100:
	s_lshl_b32 s0, s78, 9
	s_and_b32 s0, s0, 0xfffff800
	s_lshl_b32 s1, s33, 8
	v_xor_b32_e32 v4, v3, v2
	v_lshlrev_b32_e32 v2, 6, v2
	s_or_b32 s0, s1, s0
	v_and_b32_e32 v131, 48, v4
	v_and_b32_e32 v147, 0x1000, v2
	v_and_b32_e32 v145, 0x3c0, v2
	v_and_b32_e32 v146, 0xffffe000, v2
	v_add_u32_e32 v2, s0, v142
	v_lshlrev_b32_e32 v4, 1, v4
	v_ashrrev_i32_e32 v3, 31, v2
	v_and_b32_e32 v128, 48, v4
	v_lshlrev_b64 v[2:3], 6, v[2:3]
	v_lshl_add_u64 v[0:1], v[0:1], 0, v[128:129]
	v_or_b32_e32 v2, v2, v128
	v_lshl_add_u64 v[134:135], s[20:21], 0, v[0:1]
	v_mov_b32_e32 v0, 0
	s_mov_b32 s70, 1
	v_lshl_add_u64 v[132:133], s[50:51], 0, v[2:3]
	s_mov_b64 s[0:1], 0
	v_mov_b32_e32 v1, v0
	v_mov_b32_e32 v2, v0
	v_mov_b32_e32 v3, v0
	v_mov_b32_e32 v4, v0
	v_mov_b32_e32 v5, v0
	v_mov_b32_e32 v6, v0
	v_mov_b32_e32 v7, v0
	v_mov_b32_e32 v8, v0
	v_mov_b32_e32 v9, v0
	v_mov_b32_e32 v10, v0
	v_mov_b32_e32 v11, v0
	v_mov_b32_e32 v12, v0
	v_mov_b32_e32 v13, v0
	v_mov_b32_e32 v14, v0
	v_mov_b32_e32 v15, v0
	v_mov_b32_e32 v16, v0
	v_mov_b32_e32 v17, v0
	v_mov_b32_e32 v18, v0
	v_mov_b32_e32 v19, v0
	v_mov_b32_e32 v20, v0
	v_mov_b32_e32 v21, v0
	v_mov_b32_e32 v22, v0
	v_mov_b32_e32 v23, v0
	v_mov_b32_e32 v24, v0
	v_mov_b32_e32 v25, v0
	v_mov_b32_e32 v26, v0
	v_mov_b32_e32 v27, v0
	v_mov_b32_e32 v28, v0
	v_mov_b32_e32 v29, v0
	v_mov_b32_e32 v30, v0
	v_mov_b32_e32 v31, v0
	v_mov_b32_e32 v32, v0
	v_mov_b32_e32 v33, v0
	v_mov_b32_e32 v34, v0
	v_mov_b32_e32 v35, v0
	v_mov_b32_e32 v36, v0
	v_mov_b32_e32 v37, v0
	v_mov_b32_e32 v38, v0
	v_mov_b32_e32 v39, v0
	v_mov_b32_e32 v40, v0
	v_mov_b32_e32 v41, v0
	v_mov_b32_e32 v42, v0
	v_mov_b32_e32 v43, v0
	v_mov_b32_e32 v44, v0
	v_mov_b32_e32 v45, v0
	v_mov_b32_e32 v46, v0
	v_mov_b32_e32 v47, v0
	v_mov_b32_e32 v48, v0
	v_mov_b32_e32 v49, v0
	v_mov_b32_e32 v50, v0
	v_mov_b32_e32 v51, v0
	v_mov_b32_e32 v52, v0
	v_mov_b32_e32 v53, v0
	v_mov_b32_e32 v54, v0
	v_mov_b32_e32 v55, v0
	v_mov_b32_e32 v56, v0
	v_mov_b32_e32 v57, v0
	v_mov_b32_e32 v58, v0
	v_mov_b32_e32 v59, v0
	v_mov_b32_e32 v64, v0
	v_mov_b32_e32 v65, v0
	v_mov_b32_e32 v66, v0
	v_mov_b32_e32 v67, v0
	v_mov_b32_e32 v60, v0
	v_mov_b32_e32 v61, v0
	v_mov_b32_e32 v62, v0
	v_mov_b32_e32 v63, v0
	v_mov_b32_e32 v68, v0
	v_mov_b32_e32 v69, v0
	v_mov_b32_e32 v70, v0
	v_mov_b32_e32 v71, v0
	v_mov_b32_e32 v72, v0
	v_mov_b32_e32 v73, v0
	v_mov_b32_e32 v74, v0
	v_mov_b32_e32 v75, v0
	v_mov_b32_e32 v76, v0
	v_mov_b32_e32 v77, v0
	v_mov_b32_e32 v78, v0
	v_mov_b32_e32 v79, v0
	v_mov_b32_e32 v80, v0
	v_mov_b32_e32 v81, v0
	v_mov_b32_e32 v82, v0
	v_mov_b32_e32 v83, v0
	v_mov_b32_e32 v84, v0
	v_mov_b32_e32 v85, v0
	v_mov_b32_e32 v86, v0
	v_mov_b32_e32 v87, v0
	v_mov_b32_e32 v88, v0
	v_mov_b32_e32 v89, v0
	v_mov_b32_e32 v90, v0
	v_mov_b32_e32 v91, v0
	v_mov_b32_e32 v92, v0
	v_mov_b32_e32 v93, v0
	v_mov_b32_e32 v94, v0
	v_mov_b32_e32 v95, v0
	v_mov_b32_e32 v96, v0
	v_mov_b32_e32 v97, v0
	v_mov_b32_e32 v98, v0
	v_mov_b32_e32 v99, v0
	v_mov_b32_e32 v100, v0
	v_mov_b32_e32 v101, v0
	v_mov_b32_e32 v102, v0
	v_mov_b32_e32 v103, v0
	v_mov_b32_e32 v104, v0
	v_mov_b32_e32 v105, v0
	v_mov_b32_e32 v106, v0
	v_mov_b32_e32 v107, v0
	v_mov_b32_e32 v108, v0
	v_mov_b32_e32 v109, v0
	v_mov_b32_e32 v110, v0
	v_mov_b32_e32 v111, v0
	v_mov_b32_e32 v112, v0
	v_mov_b32_e32 v113, v0
	v_mov_b32_e32 v114, v0
	v_mov_b32_e32 v115, v0
	v_mov_b32_e32 v116, v0
	v_mov_b32_e32 v117, v0
	v_mov_b32_e32 v118, v0
	v_mov_b32_e32 v119, v0
	v_mov_b32_e32 v120, v0
	v_mov_b32_e32 v121, v0
	v_mov_b32_e32 v122, v0
	v_mov_b32_e32 v123, v0
	v_mov_b32_e32 v124, v0
	v_mov_b32_e32 v125, v0
	v_mov_b32_e32 v126, v0
	v_mov_b32_e32 v127, v0
	v_lshl_add_u64 v[226:227], v[132:133], 0, s[12:13]
	v_lshl_add_u64 v[228:229], v[226:227], 0, s[14:15]
	v_lshl_add_u64 v[230:231], v[228:229], 0, s[14:15]
	v_lshl_add_u64 v[232:233], v[230:231], 0, s[14:15]
	v_lshl_add_u64 v[234:235], v[134:135], 0, s[34:35]
	v_lshl_add_u64 v[236:237], v[134:135], 0, s[46:47]
	v_add3_u32 v216, v146, v145, v131
	v_add3_u32 v217, v147, v145, v131
	v_readfirstlane_b32 s30, v144
	s_nop 3
	s_add_u32 s24, s30, 0x6000
	s_mov_b32 m0, s24
	s_nop 0
	global_load_lds_dwordx4 v[226:227], off
	v_lshl_add_u64 v[226:227], v[226:227], 0, s[12:13]
	s_nop 0
	s_add_u32 s97, s24, 0x1000
	s_mov_b32 m0, s97
	s_nop 0
	global_load_lds_dwordx4 v[228:229], off
	v_lshl_add_u64 v[228:229], v[228:229], 0, s[12:13]
	s_nop 0
	s_add_u32 s97, s24, 0x2000
	s_mov_b32 m0, s97
	s_nop 0
	global_load_lds_dwordx4 v[230:231], off
	v_lshl_add_u64 v[230:231], v[230:231], 0, s[12:13]
	s_nop 0
	s_add_u32 s97, s24, 0x3000
	s_mov_b32 m0, s97
	s_nop 0
	global_load_lds_dwordx4 v[232:233], off
	v_lshl_add_u64 v[232:233], v[232:233], 0, s[12:13]
	s_nop 0
	s_add_u32 s97, s24, 0x4000
	s_mov_b32 m0, s97
	s_nop 0
	global_load_lds_dwordx4 v[234:235], off
	v_lshl_add_u64 v[234:235], v[234:235], 0, s[16:17]
	s_nop 0
	s_add_u32 s97, s24, 0x5000
	s_mov_b32 m0, s97
	s_nop 0
	global_load_lds_dwordx4 v[236:237], off
	v_lshl_add_u64 v[236:237], v[236:237], 0, s[16:17]
	s_nop 0
	s_add_u32 s24, s30, 0xc000
	s_mov_b32 m0, s24
	s_nop 0
	global_load_lds_dwordx4 v[226:227], off
	v_lshl_add_u64 v[226:227], v[226:227], 0, s[12:13]
	s_nop 0
	s_add_u32 s97, s24, 0x1000
	s_mov_b32 m0, s97
	s_nop 0
	global_load_lds_dwordx4 v[228:229], off
	v_lshl_add_u64 v[228:229], v[228:229], 0, s[12:13]
	s_nop 0
	s_add_u32 s97, s24, 0x2000
	s_mov_b32 m0, s97
	s_nop 0
	global_load_lds_dwordx4 v[230:231], off
	v_lshl_add_u64 v[230:231], v[230:231], 0, s[12:13]
	s_nop 0
	s_add_u32 s97, s24, 0x3000
	s_mov_b32 m0, s97
	s_nop 0
	global_load_lds_dwordx4 v[232:233], off
	v_lshl_add_u64 v[232:233], v[232:233], 0, s[12:13]
	s_nop 0
	s_add_u32 s97, s24, 0x4000
	s_mov_b32 m0, s97
	s_nop 0
	global_load_lds_dwordx4 v[234:235], off
	v_lshl_add_u64 v[234:235], v[234:235], 0, s[16:17]
	s_nop 0
	s_add_u32 s97, s24, 0x5000
	s_mov_b32 m0, s97
	s_nop 0
	global_load_lds_dwordx4 v[236:237], off
	v_lshl_add_u64 v[236:237], v[236:237], 0, s[16:17]
	s_nop 0
	s_waitcnt vmcnt(12) lgkmcnt(0)
	s_barrier
	ds_read_b128 v[148:151], v217 offset:16384
	ds_read_b128 v[152:155], v217 offset:17408
	ds_read_b128 v[156:159], v217 offset:18432
	ds_read_b128 v[160:163], v217 offset:19456
	ds_read_b128 v[164:167], v216 offset:0
	ds_read_b128 v[168:171], v216 offset:1024
	ds_read_b128 v[172:175], v216 offset:2048
	ds_read_b128 v[176:179], v216 offset:3072
	s_mov_b32 s18, 0
	s_movk_i32 s25, 0x6000
	s_mov_b32 s32, 0xc000
	s_mov_b32 s70, 0
.Lg1_loop:
	v_add_u32_e32 v218, s18, v216
	ds_read_b128 v[184:187], v218 offset:4096
	ds_read_b128 v[188:191], v218 offset:5120
	ds_read_b128 v[192:195], v218 offset:6144
	ds_read_b128 v[196:199], v218 offset:7168
	v_add_u32_e32 v219, s25, v216
	v_add_u32_e32 v220, s25, v217
	s_waitcnt lgkmcnt(7)
	v_mfma_f32_16x16x32_bf16 v[124:127], v[148:151], v[164:167], v[124:127]
	v_mfma_f32_16x16x32_bf16 v[120:123], v[152:155], v[164:167], v[120:123]
	v_mfma_f32_16x16x32_bf16 v[116:119], v[156:159], v[164:167], v[116:119]
	v_mfma_f32_16x16x32_bf16 v[112:115], v[160:163], v[164:167], v[112:115]
	s_waitcnt lgkmcnt(6)
	v_mfma_f32_16x16x32_bf16 v[108:111], v[148:151], v[168:171], v[108:111]
	v_mfma_f32_16x16x32_bf16 v[104:107], v[152:155], v[168:171], v[104:107]
	v_mfma_f32_16x16x32_bf16 v[100:103], v[156:159], v[168:171], v[100:103]
	v_mfma_f32_16x16x32_bf16 v[96:99], v[160:163], v[168:171], v[96:99]
	s_waitcnt lgkmcnt(5)
	v_mfma_f32_16x16x32_bf16 v[92:95], v[148:151], v[172:175], v[92:95]
	v_mfma_f32_16x16x32_bf16 v[88:91], v[152:155], v[172:175], v[88:91]
	v_mfma_f32_16x16x32_bf16 v[84:87], v[156:159], v[172:175], v[84:87]
	v_mfma_f32_16x16x32_bf16 v[80:83], v[160:163], v[172:175], v[80:83]
	s_waitcnt lgkmcnt(4)
	v_mfma_f32_16x16x32_bf16 v[76:79], v[148:151], v[176:179], v[76:79]
	v_mfma_f32_16x16x32_bf16 v[72:75], v[152:155], v[176:179], v[72:75]
	v_mfma_f32_16x16x32_bf16 v[68:71], v[156:159], v[176:179], v[68:71]
	v_mfma_f32_16x16x32_bf16 v[60:63], v[160:163], v[176:179], v[60:63]
	s_waitcnt vmcnt(6) lgkmcnt(0)
	s_barrier
	v_mfma_f32_16x16x32_bf16 v[64:67], v[148:151], v[184:187], v[64:67]
	s_add_u32 s24, s18, s30
	s_mov_b32 m0, s24
	ds_read_b128 v[200:203], v220 offset:16384
	v_mfma_f32_16x16x32_bf16 v[56:59], v[152:155], v[184:187], v[56:59]
	global_load_lds_dwordx4 v[226:227], off
	v_lshl_add_u64 v[226:227], v[226:227], 0, s[12:13]
	ds_read_b128 v[204:207], v220 offset:17408
	v_mfma_f32_16x16x32_bf16 v[52:55], v[156:159], v[184:187], v[52:55]
	s_add_u32 s97, s24, 0x1000
	s_mov_b32 m0, s97
	ds_read_b128 v[208:211], v220 offset:18432
	v_mfma_f32_16x16x32_bf16 v[48:51], v[160:163], v[184:187], v[48:51]
	global_load_lds_dwordx4 v[228:229], off
	v_lshl_add_u64 v[228:229], v[228:229], 0, s[12:13]
	ds_read_b128 v[212:215], v220 offset:19456
	v_mfma_f32_16x16x32_bf16 v[44:47], v[148:151], v[188:191], v[44:47]
	s_add_u32 s97, s24, 0x2000
	s_mov_b32 m0, s97
	ds_read_b128 v[164:167], v219 offset:0
	v_mfma_f32_16x16x32_bf16 v[40:43], v[152:155], v[188:191], v[40:43]
	global_load_lds_dwordx4 v[230:231], off
	v_lshl_add_u64 v[230:231], v[230:231], 0, s[12:13]
	ds_read_b128 v[168:171], v219 offset:1024
	v_mfma_f32_16x16x32_bf16 v[36:39], v[156:159], v[188:191], v[36:39]
	s_add_u32 s97, s24, 0x3000
	s_mov_b32 m0, s97
	ds_read_b128 v[172:175], v219 offset:2048
	v_mfma_f32_16x16x32_bf16 v[32:35], v[160:163], v[188:191], v[32:35]
	global_load_lds_dwordx4 v[232:233], off
	v_lshl_add_u64 v[232:233], v[232:233], 0, s[12:13]
	ds_read_b128 v[176:179], v219 offset:3072
	v_mfma_f32_16x16x32_bf16 v[28:31], v[148:151], v[192:195], v[28:31]
	s_add_u32 s97, s24, 0x4000
	s_mov_b32 m0, s97
	v_mfma_f32_16x16x32_bf16 v[24:27], v[152:155], v[192:195], v[24:27]
	global_load_lds_dwordx4 v[234:235], off
	v_lshl_add_u64 v[234:235], v[234:235], 0, s[16:17]
	v_mfma_f32_16x16x32_bf16 v[20:23], v[156:159], v[192:195], v[20:23]
	s_add_u32 s97, s24, 0x5000
	s_mov_b32 m0, s97
	v_mfma_f32_16x16x32_bf16 v[16:19], v[160:163], v[192:195], v[16:19]
	global_load_lds_dwordx4 v[236:237], off
	v_lshl_add_u64 v[236:237], v[236:237], 0, s[16:17]
	v_mfma_f32_16x16x32_bf16 v[12:15], v[148:151], v[196:199], v[12:15]
	v_mfma_f32_16x16x32_bf16 v[8:11], v[152:155], v[196:199], v[8:11]
	v_mfma_f32_16x16x32_bf16 v[4:7], v[156:159], v[196:199], v[4:7]
	v_mfma_f32_16x16x32_bf16 v[0:3], v[160:163], v[196:199], v[0:3]
	s_mov_b32 s24, s18
	s_mov_b32 s18, s25
	s_mov_b32 s25, s32
	s_mov_b32 s32, s24
	v_add_u32_e32 v218, s18, v216
	ds_read_b128 v[184:187], v218 offset:4096
	ds_read_b128 v[188:191], v218 offset:5120
	ds_read_b128 v[192:195], v218 offset:6144
	ds_read_b128 v[196:199], v218 offset:7168
	v_add_u32_e32 v219, s25, v216
	v_add_u32_e32 v220, s25, v217
	s_waitcnt lgkmcnt(7)
	v_mfma_f32_16x16x32_bf16 v[124:127], v[200:203], v[164:167], v[124:127]
	v_mfma_f32_16x16x32_bf16 v[120:123], v[204:207], v[164:167], v[120:123]
	v_mfma_f32_16x16x32_bf16 v[116:119], v[208:211], v[164:167], v[116:119]
	v_mfma_f32_16x16x32_bf16 v[112:115], v[212:215], v[164:167], v[112:115]
	s_waitcnt lgkmcnt(6)
	v_mfma_f32_16x16x32_bf16 v[108:111], v[200:203], v[168:171], v[108:111]
	v_mfma_f32_16x16x32_bf16 v[104:107], v[204:207], v[168:171], v[104:107]
	v_mfma_f32_16x16x32_bf16 v[100:103], v[208:211], v[168:171], v[100:103]
	v_mfma_f32_16x16x32_bf16 v[96:99], v[212:215], v[168:171], v[96:99]
	s_waitcnt lgkmcnt(5)
	v_mfma_f32_16x16x32_bf16 v[92:95], v[200:203], v[172:175], v[92:95]
	v_mfma_f32_16x16x32_bf16 v[88:91], v[204:207], v[172:175], v[88:91]
	v_mfma_f32_16x16x32_bf16 v[84:87], v[208:211], v[172:175], v[84:87]
	v_mfma_f32_16x16x32_bf16 v[80:83], v[212:215], v[172:175], v[80:83]
	s_waitcnt lgkmcnt(4)
	v_mfma_f32_16x16x32_bf16 v[76:79], v[200:203], v[176:179], v[76:79]
	v_mfma_f32_16x16x32_bf16 v[72:75], v[204:207], v[176:179], v[72:75]
	v_mfma_f32_16x16x32_bf16 v[68:71], v[208:211], v[176:179], v[68:71]
	v_mfma_f32_16x16x32_bf16 v[60:63], v[212:215], v[176:179], v[60:63]
	s_waitcnt vmcnt(6) lgkmcnt(0)
	s_barrier
	v_mfma_f32_16x16x32_bf16 v[64:67], v[200:203], v[184:187], v[64:67]
	s_add_u32 s24, s18, s30
	s_mov_b32 m0, s24
	ds_read_b128 v[148:151], v220 offset:16384
	v_mfma_f32_16x16x32_bf16 v[56:59], v[204:207], v[184:187], v[56:59]
	global_load_lds_dwordx4 v[226:227], off
	v_lshl_add_u64 v[226:227], v[226:227], 0, s[12:13]
	ds_read_b128 v[152:155], v220 offset:17408
	v_mfma_f32_16x16x32_bf16 v[52:55], v[208:211], v[184:187], v[52:55]
	s_add_u32 s97, s24, 0x1000
	s_mov_b32 m0, s97
	ds_read_b128 v[156:159], v220 offset:18432
	v_mfma_f32_16x16x32_bf16 v[48:51], v[212:215], v[184:187], v[48:51]
	global_load_lds_dwordx4 v[228:229], off
	v_lshl_add_u64 v[228:229], v[228:229], 0, s[12:13]
	ds_read_b128 v[160:163], v220 offset:19456
	v_mfma_f32_16x16x32_bf16 v[44:47], v[200:203], v[188:191], v[44:47]
	s_add_u32 s97, s24, 0x2000
	s_mov_b32 m0, s97
	ds_read_b128 v[164:167], v219 offset:0
	v_mfma_f32_16x16x32_bf16 v[40:43], v[204:207], v[188:191], v[40:43]
	global_load_lds_dwordx4 v[230:231], off
	v_lshl_add_u64 v[230:231], v[230:231], 0, s[12:13]
	ds_read_b128 v[168:171], v219 offset:1024
	v_mfma_f32_16x16x32_bf16 v[36:39], v[208:211], v[188:191], v[36:39]
	s_add_u32 s97, s24, 0x3000
	s_mov_b32 m0, s97
	ds_read_b128 v[172:175], v219 offset:2048
	v_mfma_f32_16x16x32_bf16 v[32:35], v[212:215], v[188:191], v[32:35]
	global_load_lds_dwordx4 v[232:233], off
	v_lshl_add_u64 v[232:233], v[232:233], 0, s[12:13]
	ds_read_b128 v[176:179], v219 offset:3072
	v_mfma_f32_16x16x32_bf16 v[28:31], v[200:203], v[192:195], v[28:31]
	s_add_u32 s97, s24, 0x4000
	s_mov_b32 m0, s97
	v_mfma_f32_16x16x32_bf16 v[24:27], v[204:207], v[192:195], v[24:27]
	global_load_lds_dwordx4 v[234:235], off
	v_lshl_add_u64 v[234:235], v[234:235], 0, s[16:17]
	v_mfma_f32_16x16x32_bf16 v[20:23], v[208:211], v[192:195], v[20:23]
	s_add_u32 s97, s24, 0x5000
	s_mov_b32 m0, s97
	v_mfma_f32_16x16x32_bf16 v[16:19], v[212:215], v[192:195], v[16:19]
	global_load_lds_dwordx4 v[236:237], off
	v_lshl_add_u64 v[236:237], v[236:237], 0, s[16:17]
	v_mfma_f32_16x16x32_bf16 v[12:15], v[200:203], v[196:199], v[12:15]
	v_mfma_f32_16x16x32_bf16 v[8:11], v[204:207], v[196:199], v[8:11]
	v_mfma_f32_16x16x32_bf16 v[4:7], v[208:211], v[196:199], v[4:7]
	v_mfma_f32_16x16x32_bf16 v[0:3], v[212:215], v[196:199], v[0:3]
	s_mov_b32 s24, s18
	s_mov_b32 s18, s25
	s_mov_b32 s25, s32
	s_mov_b32 s32, s24
	s_add_i32 s70, s70, 1
	s_cmp_lt_u32 s70, 14
	s_cbranch_scc1 .Lg1_loop
	v_add_u32_e32 v218, s18, v216
	ds_read_b128 v[184:187], v218 offset:4096
	ds_read_b128 v[188:191], v218 offset:5120
	ds_read_b128 v[192:195], v218 offset:6144
	ds_read_b128 v[196:199], v218 offset:7168
	v_add_u32_e32 v219, s25, v216
	v_add_u32_e32 v220, s25, v217
	s_waitcnt lgkmcnt(7)
	v_mfma_f32_16x16x32_bf16 v[124:127], v[148:151], v[164:167], v[124:127]
	v_mfma_f32_16x16x32_bf16 v[120:123], v[152:155], v[164:167], v[120:123]
	v_mfma_f32_16x16x32_bf16 v[116:119], v[156:159], v[164:167], v[116:119]
	v_mfma_f32_16x16x32_bf16 v[112:115], v[160:163], v[164:167], v[112:115]
	s_waitcnt lgkmcnt(6)
	v_mfma_f32_16x16x32_bf16 v[108:111], v[148:151], v[168:171], v[108:111]
	v_mfma_f32_16x16x32_bf16 v[104:107], v[152:155], v[168:171], v[104:107]
	v_mfma_f32_16x16x32_bf16 v[100:103], v[156:159], v[168:171], v[100:103]
	v_mfma_f32_16x16x32_bf16 v[96:99], v[160:163], v[168:171], v[96:99]
	s_waitcnt lgkmcnt(5)
	v_mfma_f32_16x16x32_bf16 v[92:95], v[148:151], v[172:175], v[92:95]
	v_mfma_f32_16x16x32_bf16 v[88:91], v[152:155], v[172:175], v[88:91]
	v_mfma_f32_16x16x32_bf16 v[84:87], v[156:159], v[172:175], v[84:87]
	v_mfma_f32_16x16x32_bf16 v[80:83], v[160:163], v[172:175], v[80:83]
	s_waitcnt lgkmcnt(4)
	v_mfma_f32_16x16x32_bf16 v[76:79], v[148:151], v[176:179], v[76:79]
	v_mfma_f32_16x16x32_bf16 v[72:75], v[152:155], v[176:179], v[72:75]
	v_mfma_f32_16x16x32_bf16 v[68:71], v[156:159], v[176:179], v[68:71]
	v_mfma_f32_16x16x32_bf16 v[60:63], v[160:163], v[176:179], v[60:63]
	s_waitcnt vmcnt(6) lgkmcnt(0)
	s_barrier
	v_mfma_f32_16x16x32_bf16 v[64:67], v[148:151], v[184:187], v[64:67]
	s_add_u32 s24, s18, s30
	s_mov_b32 m0, s24
	ds_read_b128 v[200:203], v220 offset:16384
	v_mfma_f32_16x16x32_bf16 v[56:59], v[152:155], v[184:187], v[56:59]
	global_load_lds_dwordx4 v[226:227], off
	v_lshl_add_u64 v[226:227], v[226:227], 0, s[12:13]
	ds_read_b128 v[204:207], v220 offset:17408
	v_mfma_f32_16x16x32_bf16 v[52:55], v[156:159], v[184:187], v[52:55]
	s_add_u32 s97, s24, 0x1000
	s_mov_b32 m0, s97
	ds_read_b128 v[208:211], v220 offset:18432
	v_mfma_f32_16x16x32_bf16 v[48:51], v[160:163], v[184:187], v[48:51]
	global_load_lds_dwordx4 v[228:229], off
	v_lshl_add_u64 v[228:229], v[228:229], 0, s[12:13]
	ds_read_b128 v[212:215], v220 offset:19456
	v_mfma_f32_16x16x32_bf16 v[44:47], v[148:151], v[188:191], v[44:47]
	s_add_u32 s97, s24, 0x2000
	s_mov_b32 m0, s97
	ds_read_b128 v[164:167], v219 offset:0
	v_mfma_f32_16x16x32_bf16 v[40:43], v[152:155], v[188:191], v[40:43]
	global_load_lds_dwordx4 v[230:231], off
	v_lshl_add_u64 v[230:231], v[230:231], 0, s[12:13]
	ds_read_b128 v[168:171], v219 offset:1024
	v_mfma_f32_16x16x32_bf16 v[36:39], v[156:159], v[188:191], v[36:39]
	s_add_u32 s97, s24, 0x3000
	s_mov_b32 m0, s97
	ds_read_b128 v[172:175], v219 offset:2048
	v_mfma_f32_16x16x32_bf16 v[32:35], v[160:163], v[188:191], v[32:35]
	global_load_lds_dwordx4 v[232:233], off
	v_lshl_add_u64 v[232:233], v[232:233], 0, s[12:13]
	ds_read_b128 v[176:179], v219 offset:3072
	v_mfma_f32_16x16x32_bf16 v[28:31], v[148:151], v[192:195], v[28:31]
	s_add_u32 s97, s24, 0x4000
	s_mov_b32 m0, s97
	v_mfma_f32_16x16x32_bf16 v[24:27], v[152:155], v[192:195], v[24:27]
	global_load_lds_dwordx4 v[234:235], off
	v_lshl_add_u64 v[234:235], v[234:235], 0, s[16:17]
	v_mfma_f32_16x16x32_bf16 v[20:23], v[156:159], v[192:195], v[20:23]
	s_add_u32 s97, s24, 0x5000
	s_mov_b32 m0, s97
	v_mfma_f32_16x16x32_bf16 v[16:19], v[160:163], v[192:195], v[16:19]
	global_load_lds_dwordx4 v[236:237], off
	v_lshl_add_u64 v[236:237], v[236:237], 0, s[16:17]
	v_mfma_f32_16x16x32_bf16 v[12:15], v[148:151], v[196:199], v[12:15]
	v_mfma_f32_16x16x32_bf16 v[8:11], v[152:155], v[196:199], v[8:11]
	v_mfma_f32_16x16x32_bf16 v[4:7], v[156:159], v[196:199], v[4:7]
	v_mfma_f32_16x16x32_bf16 v[0:3], v[160:163], v[196:199], v[0:3]
	s_mov_b32 s24, s18
	s_mov_b32 s18, s25
	s_mov_b32 s25, s32
	s_mov_b32 s32, s24
	v_add_u32_e32 v218, s18, v216
	ds_read_b128 v[184:187], v218 offset:4096
	ds_read_b128 v[188:191], v218 offset:5120
	ds_read_b128 v[192:195], v218 offset:6144
	ds_read_b128 v[196:199], v218 offset:7168
	v_add_u32_e32 v219, s25, v216
	v_add_u32_e32 v220, s25, v217
	s_waitcnt lgkmcnt(7)
	v_mfma_f32_16x16x32_bf16 v[124:127], v[200:203], v[164:167], v[124:127]
	v_mfma_f32_16x16x32_bf16 v[120:123], v[204:207], v[164:167], v[120:123]
	v_mfma_f32_16x16x32_bf16 v[116:119], v[208:211], v[164:167], v[116:119]
	v_mfma_f32_16x16x32_bf16 v[112:115], v[212:215], v[164:167], v[112:115]
	s_waitcnt lgkmcnt(6)
	v_mfma_f32_16x16x32_bf16 v[108:111], v[200:203], v[168:171], v[108:111]
	v_mfma_f32_16x16x32_bf16 v[104:107], v[204:207], v[168:171], v[104:107]
	v_mfma_f32_16x16x32_bf16 v[100:103], v[208:211], v[168:171], v[100:103]
	v_mfma_f32_16x16x32_bf16 v[96:99], v[212:215], v[168:171], v[96:99]
	s_waitcnt lgkmcnt(5)
	v_mfma_f32_16x16x32_bf16 v[92:95], v[200:203], v[172:175], v[92:95]
	v_mfma_f32_16x16x32_bf16 v[88:91], v[204:207], v[172:175], v[88:91]
	v_mfma_f32_16x16x32_bf16 v[84:87], v[208:211], v[172:175], v[84:87]
	v_mfma_f32_16x16x32_bf16 v[80:83], v[212:215], v[172:175], v[80:83]
	s_waitcnt lgkmcnt(4)
	v_mfma_f32_16x16x32_bf16 v[76:79], v[200:203], v[176:179], v[76:79]
	v_mfma_f32_16x16x32_bf16 v[72:75], v[204:207], v[176:179], v[72:75]
	v_mfma_f32_16x16x32_bf16 v[68:71], v[208:211], v[176:179], v[68:71]
	v_mfma_f32_16x16x32_bf16 v[60:63], v[212:215], v[176:179], v[60:63]
	s_waitcnt vmcnt(6) lgkmcnt(0)
	s_barrier
	v_mfma_f32_16x16x32_bf16 v[64:67], v[200:203], v[184:187], v[64:67]
	ds_read_b128 v[148:151], v220 offset:16384
	v_mfma_f32_16x16x32_bf16 v[56:59], v[204:207], v[184:187], v[56:59]
	ds_read_b128 v[152:155], v220 offset:17408
	v_mfma_f32_16x16x32_bf16 v[52:55], v[208:211], v[184:187], v[52:55]
	ds_read_b128 v[156:159], v220 offset:18432
	v_mfma_f32_16x16x32_bf16 v[48:51], v[212:215], v[184:187], v[48:51]
	ds_read_b128 v[160:163], v220 offset:19456
	v_mfma_f32_16x16x32_bf16 v[44:47], v[200:203], v[188:191], v[44:47]
	ds_read_b128 v[164:167], v219 offset:0
	v_mfma_f32_16x16x32_bf16 v[40:43], v[204:207], v[188:191], v[40:43]
	ds_read_b128 v[168:171], v219 offset:1024
	v_mfma_f32_16x16x32_bf16 v[36:39], v[208:211], v[188:191], v[36:39]
	ds_read_b128 v[172:175], v219 offset:2048
	v_mfma_f32_16x16x32_bf16 v[32:35], v[212:215], v[188:191], v[32:35]
	ds_read_b128 v[176:179], v219 offset:3072
	v_mfma_f32_16x16x32_bf16 v[28:31], v[200:203], v[192:195], v[28:31]
	v_mfma_f32_16x16x32_bf16 v[24:27], v[204:207], v[192:195], v[24:27]
	v_mfma_f32_16x16x32_bf16 v[20:23], v[208:211], v[192:195], v[20:23]
	v_mfma_f32_16x16x32_bf16 v[16:19], v[212:215], v[192:195], v[16:19]
	v_mfma_f32_16x16x32_bf16 v[12:15], v[200:203], v[196:199], v[12:15]
	v_mfma_f32_16x16x32_bf16 v[8:11], v[204:207], v[196:199], v[8:11]
	v_mfma_f32_16x16x32_bf16 v[4:7], v[208:211], v[196:199], v[4:7]
	v_mfma_f32_16x16x32_bf16 v[0:3], v[212:215], v[196:199], v[0:3]
	s_mov_b32 s24, s18
	s_mov_b32 s18, s25
	s_mov_b32 s25, s32
	s_mov_b32 s32, s24
	v_add_u32_e32 v218, s18, v216
	ds_read_b128 v[184:187], v218 offset:4096
	ds_read_b128 v[188:191], v218 offset:5120
	ds_read_b128 v[192:195], v218 offset:6144
	ds_read_b128 v[196:199], v218 offset:7168
	v_add_u32_e32 v219, s25, v216
	v_add_u32_e32 v220, s25, v217
	s_waitcnt lgkmcnt(7)
	v_mfma_f32_16x16x32_bf16 v[124:127], v[148:151], v[164:167], v[124:127]
	v_mfma_f32_16x16x32_bf16 v[120:123], v[152:155], v[164:167], v[120:123]
	v_mfma_f32_16x16x32_bf16 v[116:119], v[156:159], v[164:167], v[116:119]
	v_mfma_f32_16x16x32_bf16 v[112:115], v[160:163], v[164:167], v[112:115]
	s_waitcnt lgkmcnt(6)
	v_mfma_f32_16x16x32_bf16 v[108:111], v[148:151], v[168:171], v[108:111]
	v_mfma_f32_16x16x32_bf16 v[104:107], v[152:155], v[168:171], v[104:107]
	v_mfma_f32_16x16x32_bf16 v[100:103], v[156:159], v[168:171], v[100:103]
	v_mfma_f32_16x16x32_bf16 v[96:99], v[160:163], v[168:171], v[96:99]
	s_waitcnt lgkmcnt(5)
	v_mfma_f32_16x16x32_bf16 v[92:95], v[148:151], v[172:175], v[92:95]
	v_mfma_f32_16x16x32_bf16 v[88:91], v[152:155], v[172:175], v[88:91]
	v_mfma_f32_16x16x32_bf16 v[84:87], v[156:159], v[172:175], v[84:87]
	v_mfma_f32_16x16x32_bf16 v[80:83], v[160:163], v[172:175], v[80:83]
	s_waitcnt lgkmcnt(4)
	v_mfma_f32_16x16x32_bf16 v[76:79], v[148:151], v[176:179], v[76:79]
	v_mfma_f32_16x16x32_bf16 v[72:75], v[152:155], v[176:179], v[72:75]
	v_mfma_f32_16x16x32_bf16 v[68:71], v[156:159], v[176:179], v[68:71]
	v_mfma_f32_16x16x32_bf16 v[60:63], v[160:163], v[176:179], v[60:63]
	s_waitcnt vmcnt(0) lgkmcnt(0)
	s_barrier
	v_mfma_f32_16x16x32_bf16 v[64:67], v[148:151], v[184:187], v[64:67]
	ds_read_b128 v[200:203], v220 offset:16384
	v_mfma_f32_16x16x32_bf16 v[56:59], v[152:155], v[184:187], v[56:59]
	ds_read_b128 v[204:207], v220 offset:17408
	v_mfma_f32_16x16x32_bf16 v[52:55], v[156:159], v[184:187], v[52:55]
	ds_read_b128 v[208:211], v220 offset:18432
	v_mfma_f32_16x16x32_bf16 v[48:51], v[160:163], v[184:187], v[48:51]
	ds_read_b128 v[212:215], v220 offset:19456
	v_mfma_f32_16x16x32_bf16 v[44:47], v[148:151], v[188:191], v[44:47]
	ds_read_b128 v[164:167], v219 offset:0
	v_mfma_f32_16x16x32_bf16 v[40:43], v[152:155], v[188:191], v[40:43]
	ds_read_b128 v[168:171], v219 offset:1024
	v_mfma_f32_16x16x32_bf16 v[36:39], v[156:159], v[188:191], v[36:39]
	ds_read_b128 v[172:175], v219 offset:2048
	v_mfma_f32_16x16x32_bf16 v[32:35], v[160:163], v[188:191], v[32:35]
	ds_read_b128 v[176:179], v219 offset:3072
	v_mfma_f32_16x16x32_bf16 v[28:31], v[148:151], v[192:195], v[28:31]
	v_mfma_f32_16x16x32_bf16 v[24:27], v[152:155], v[192:195], v[24:27]
	v_mfma_f32_16x16x32_bf16 v[20:23], v[156:159], v[192:195], v[20:23]
	v_mfma_f32_16x16x32_bf16 v[16:19], v[160:163], v[192:195], v[16:19]
	v_mfma_f32_16x16x32_bf16 v[12:15], v[148:151], v[196:199], v[12:15]
	v_mfma_f32_16x16x32_bf16 v[8:11], v[152:155], v[196:199], v[8:11]
	v_mfma_f32_16x16x32_bf16 v[4:7], v[156:159], v[196:199], v[4:7]
	v_mfma_f32_16x16x32_bf16 v[0:3], v[160:163], v[196:199], v[0:3]
	s_mov_b32 s24, s18
	s_mov_b32 s18, s25
	s_mov_b32 s25, s32
	s_mov_b32 s32, s24
	v_add_u32_e32 v218, s18, v216
	ds_read_b128 v[184:187], v218 offset:4096
	ds_read_b128 v[188:191], v218 offset:5120
	ds_read_b128 v[192:195], v218 offset:6144
	ds_read_b128 v[196:199], v218 offset:7168
	s_waitcnt lgkmcnt(7)
	v_mfma_f32_16x16x32_bf16 v[124:127], v[200:203], v[164:167], v[124:127]
	v_mfma_f32_16x16x32_bf16 v[120:123], v[204:207], v[164:167], v[120:123]
	v_mfma_f32_16x16x32_bf16 v[116:119], v[208:211], v[164:167], v[116:119]
	v_mfma_f32_16x16x32_bf16 v[112:115], v[212:215], v[164:167], v[112:115]
	s_waitcnt lgkmcnt(6)
	v_mfma_f32_16x16x32_bf16 v[108:111], v[200:203], v[168:171], v[108:111]
	v_mfma_f32_16x16x32_bf16 v[104:107], v[204:207], v[168:171], v[104:107]
	v_mfma_f32_16x16x32_bf16 v[100:103], v[208:211], v[168:171], v[100:103]
	v_mfma_f32_16x16x32_bf16 v[96:99], v[212:215], v[168:171], v[96:99]
	s_waitcnt lgkmcnt(5)
	v_mfma_f32_16x16x32_bf16 v[92:95], v[200:203], v[172:175], v[92:95]
	v_mfma_f32_16x16x32_bf16 v[88:91], v[204:207], v[172:175], v[88:91]
	v_mfma_f32_16x16x32_bf16 v[84:87], v[208:211], v[172:175], v[84:87]
	v_mfma_f32_16x16x32_bf16 v[80:83], v[212:215], v[172:175], v[80:83]
	s_waitcnt lgkmcnt(4)
	v_mfma_f32_16x16x32_bf16 v[76:79], v[200:203], v[176:179], v[76:79]
	v_mfma_f32_16x16x32_bf16 v[72:75], v[204:207], v[176:179], v[72:75]
	v_mfma_f32_16x16x32_bf16 v[68:71], v[208:211], v[176:179], v[68:71]
	v_mfma_f32_16x16x32_bf16 v[60:63], v[212:215], v[176:179], v[60:63]
	s_waitcnt lgkmcnt(0)
	s_barrier
	v_mfma_f32_16x16x32_bf16 v[64:67], v[200:203], v[184:187], v[64:67]
	v_mfma_f32_16x16x32_bf16 v[56:59], v[204:207], v[184:187], v[56:59]
	v_mfma_f32_16x16x32_bf16 v[52:55], v[208:211], v[184:187], v[52:55]
	v_mfma_f32_16x16x32_bf16 v[48:51], v[212:215], v[184:187], v[48:51]
	v_mfma_f32_16x16x32_bf16 v[44:47], v[200:203], v[188:191], v[44:47]
	v_mfma_f32_16x16x32_bf16 v[40:43], v[204:207], v[188:191], v[40:43]
	v_mfma_f32_16x16x32_bf16 v[36:39], v[208:211], v[188:191], v[36:39]
	v_mfma_f32_16x16x32_bf16 v[32:35], v[212:215], v[188:191], v[32:35]
	v_mfma_f32_16x16x32_bf16 v[28:31], v[200:203], v[192:195], v[28:31]
	v_mfma_f32_16x16x32_bf16 v[24:27], v[204:207], v[192:195], v[24:27]
	v_mfma_f32_16x16x32_bf16 v[20:23], v[208:211], v[192:195], v[20:23]
	v_mfma_f32_16x16x32_bf16 v[16:19], v[212:215], v[192:195], v[16:19]
	v_mfma_f32_16x16x32_bf16 v[12:15], v[200:203], v[196:199], v[12:15]
	v_mfma_f32_16x16x32_bf16 v[8:11], v[204:207], v[196:199], v[8:11]
	v_mfma_f32_16x16x32_bf16 v[4:7], v[208:211], v[196:199], v[4:7]
	v_mfma_f32_16x16x32_bf16 v[0:3], v[212:215], v[196:199], v[0:3]
	s_mov_b32 s24, s18
	s_mov_b32 s18, s25
	s_mov_b32 s25, s32
	s_mov_b32 s32, s24
	s_add_i32 s0, s87, s80
	s_cmp_gt_i32 s0, 63
	s_cselect_b32 s1, s79, 0
	s_cselect_b32 s87, s29, s0
	s_add_i32 s78, s1, s78
	s_max_i32 s0, s87, s78
	s_cmp_gt_i32 s0, 63
	s_cselect_b64 s[70:71], -1, 0
	s_cmp_lt_i32 s0, 64
	s_cbranch_scc0 .LBB0_104
	s_lshl_b32 s0, s78, 1
	s_and_b32 s0, s0, 0xfffff8
	s_and_b32 s1, s87, 7
	s_or_b32 s0, s0, s1
	s_lshl_b32 s1, s78, 3
	s_and_b32 s1, s1, 24
	s_lshr_b32 s24, s87, 3
	s_add_i32 s1, s1, s24
	v_lshl_add_u32 v132, s0, 8, v142
	v_ashrrev_i32_e32 v133, 31, v132
	v_lshl_add_u32 v134, s1, 7, v142
	v_lshlrev_b64 v[132:133], 6, v[132:133]
	v_ashrrev_i32_e32 v135, 31, v134
	v_lshl_add_u64 v[132:133], s[50:51], 0, v[132:133]
	v_mov_b32_e32 v131, v129
	v_lshlrev_b64 v[134:135], 6, v[134:135]
	v_readfirstlane_b32 s0, v144
	v_lshl_add_u64 v[132:133], v[132:133], 0, v[130:131]
	v_lshl_add_u64 v[134:135], s[4:5], 0, v[134:135]
	s_mov_b32 m0, s0
	v_readfirstlane_b32 s0, v143
	v_lshl_add_u64 v[130:131], v[134:135], 0, v[130:131]
	global_load_lds_dwordx4 v[132:133], off
	v_lshl_add_u64 v[134:135], v[132:133], 0, s[14:15]
	s_mov_b32 m0, s0
	v_readfirstlane_b32 s0, v139
	global_load_lds_dwordx4 v[134:135], off
	v_lshl_add_u64 v[134:135], v[132:133], 0, s[8:9]
	s_mov_b32 m0, s0
	v_readfirstlane_b32 s0, v138
	global_load_lds_dwordx4 v[134:135], off
	v_lshl_add_u64 v[132:133], v[132:133], 0, s[10:11]
	s_mov_b32 m0, s0
	v_readfirstlane_b32 s0, v137
	global_load_lds_dwordx4 v[132:133], off
	s_mov_b32 m0, s0
	v_readfirstlane_b32 s0, v136
	global_load_lds_dwordx4 v[130:131], off
	v_lshl_add_u64 v[130:131], v[130:131], 0, s[6:7]
	s_mov_b32 m0, s0
	s_nop 0
	global_load_lds_dwordx4 v[130:131], off

.LBB0_251:
	s_cmpk_gt_i32 s2, 0xa0
	v_writelane_b32 v244, s94, 4
	s_nop 1
	v_writelane_b32 v244, s95, 5
	s_cbranch_scc1 .LBB0_411
	s_add_u32 s4, s20, 0x10200000
	s_addc_u32 s5, s21, 0
	s_add_u32 s6, s20, 0x10c40000
	s_addc_u32 s7, s21, 0
	s_lshl_b32 s0, s2, 8
	s_add_i32 s29, s0, 0xffffe000
	s_lshl_b32 s84, s22, 8
	s_lshl_b32 s85, s2, 7
	s_lshl_b32 s86, s22, 7
	v_mov_b32_e32 v129, 0
	s_mov_b64 s[8:9], 0x1000
	s_mov_b64 s[98:99], 0x1000
	s_mov_b64 s[10:11], 0x200000
	s_mov_b64 s[12:13], 0x201000
	s_mov_b64 s[14:15], 0x202000
	s_mov_b64 s[16:17], 0x203000
	s_mov_b64 s[34:35], 0x404000
	s_mov_b64 s[46:47], 0x405000
	s_mov_b64 s[62:63], 0x406000
	s_mov_b64 s[64:65], 0x407000
	s_mov_b64 s[68:69], 0x10242000
	s_mov_b64 s[70:71], 0x10243000
	s_movk_i32 s87, 0x7fff
	s_movk_i32 s90, 0x1800
	s_mov_b64 s[72:73], 0x8292000
	s_movk_i32 s91, 0x1fff
	s_movk_i32 s92, 0x1ffc
	s_mov_b64 s[74:75], 0x8100000
	s_movk_i32 s93, 0x80
	s_movk_i32 s94, 0x110
	s_brev_b32 s95, 8
	v_mov_b32_e32 v140, 0x70
	s_mov_b32 s96, s2
	s_branch .LBB0_255

.LBB0_255:
	s_cmp_gt_i32 s96, 31
	s_mov_b64 s[0:1], -1
	s_cbranch_scc0 .LBB0_261
	v_mov_b32_e32 v36, v181
	v_mov_b32_e32 v12, v181
	s_lshl_b32 s33, s96, 8
	v_lshlrev_b32_e32 v13, 3, v12
	v_ashrrev_i32_e32 v0, 2, v12
	v_bitop3_b32 v1, v13, 24, v12 bitop3:0x48
	s_addk_i32 s33, 0xe000
	v_lshlrev_b32_e32 v128, 1, v1
	v_ashrrev_i32_e32 v1, 31, v0
	v_add_u32_e32 v2, s33, v0
	v_lshlrev_b64 v[4:5], 6, v[0:1]
	v_ashrrev_i32_e32 v3, 31, v2
	v_lshl_add_u64 v[6:7], s[4:5], 0, v[4:5]
	v_lshlrev_b64 v[2:3], 6, v[2:3]
	v_lshl_add_u64 v[6:7], v[6:7], 0, v[128:129]
	s_mov_b64 s[0:1], 0x40000
	v_lshlrev_b32_e32 v37, 4, v12
	v_lshl_add_u64 v[2:3], s[50:51], 0, v[2:3]
	v_lshl_add_u64 v[8:9], v[6:7], 0, s[0:1]
	v_readfirstlane_b32 s0, v37
	v_add_u32_e32 v1, 0x1000, v37
	v_lshl_add_u64 v[2:3], v[2:3], 0, v[128:129]
	s_mov_b32 m0, s0
	v_readfirstlane_b32 s0, v1
	s_waitcnt vmcnt(0)
	s_barrier
	global_load_lds_dwordx4 v[2:3], off
	v_lshl_add_u64 v[10:11], v[2:3], 0, s[98:99]
	s_mov_b32 m0, s0
	s_mov_b64 s[0:1], 0x2000
	v_add_u32_e32 v1, 0x2000, v37
	global_load_lds_dwordx4 v[10:11], off
	v_lshl_add_u64 v[10:11], v[2:3], 0, s[0:1]
	v_readfirstlane_b32 s0, v1
	s_mov_b32 m0, s0
	s_mov_b64 s[0:1], 0x3000
	v_add_u32_e32 v1, 0x3000, v37
	v_lshl_add_u64 v[2:3], v[2:3], 0, s[0:1]
	v_readfirstlane_b32 s0, v1
	v_add_u32_e32 v1, 0x4000, v37
	global_load_lds_dwordx4 v[10:11], off
	s_mov_b32 m0, s0
	v_readfirstlane_b32 s0, v1
	global_load_lds_dwordx4 v[2:3], off
	s_mov_b32 m0, s0
	s_mov_b64 s[0:1], 0x41000
	v_add_u32_e32 v1, 0x5000, v37
	v_lshl_add_u64 v[2:3], v[6:7], 0, s[0:1]
	v_readfirstlane_b32 s0, v1
	global_load_lds_dwordx4 v[8:9], off
	s_mov_b32 m0, s0
	v_lshlrev_b32_e32 v1, 6, v12
	global_load_lds_dwordx4 v[2:3], off
	v_xor_b32_e32 v2, v13, v12
	v_add_u32_e32 v0, s29, v0
	v_and_b32_e32 v40, 0x1000, v1
	v_and_b32_e32 v39, 0x3c0, v1
	v_and_b32_e32 v41, 0xffffe000, v1
	v_ashrrev_i32_e32 v1, 31, v0
	v_lshlrev_b32_e32 v2, 1, v2
	v_lshlrev_b64 v[0:1], 6, v[0:1]
	v_and_b32_e32 v2, 48, v2
	v_or_b32_e32 v0, v0, v2
	v_lshl_add_u64 v[32:33], s[50:51], 0, v[0:1]
	v_or_b32_e32 v4, v4, v2
	v_mov_b32_e32 v0, 0
	s_mov_b32 s76, 1
	v_bitop3_b32 v38, v13, 48, v12 bitop3:0x48
	v_lshl_add_u64 v[34:35], s[20:21], 0, v[4:5]
	s_mov_b64 s[0:1], 0
	s_mov_b64 s[100:101], 0
	v_mov_b32_e32 v1, v0
	v_mov_b32_e32 v2, v0
	v_mov_b32_e32 v3, v0
	v_mov_b32_e32 v4, v0
	v_mov_b32_e32 v5, v0
	v_mov_b32_e32 v6, v0
	v_mov_b32_e32 v7, v0
	v_mov_b32_e32 v8, v0
	v_mov_b32_e32 v9, v0
	v_mov_b32_e32 v10, v0
	v_mov_b32_e32 v11, v0
	v_mov_b32_e32 v12, v0
	v_mov_b32_e32 v13, v0
	v_mov_b32_e32 v14, v0
	v_mov_b32_e32 v15, v0
	v_mov_b32_e32 v16, v0
	v_mov_b32_e32 v17, v0
	v_mov_b32_e32 v18, v0
	v_mov_b32_e32 v19, v0
	v_mov_b32_e32 v20, v0
	v_mov_b32_e32 v21, v0
	v_mov_b32_e32 v22, v0
	v_mov_b32_e32 v23, v0
	v_mov_b32_e32 v24, v0
	v_mov_b32_e32 v25, v0
	v_mov_b32_e32 v26, v0
	v_mov_b32_e32 v27, v0
	v_mov_b32_e32 v28, v0
	v_mov_b32_e32 v29, v0
	v_mov_b32_e32 v30, v0
	v_mov_b32_e32 v31, v0
	s_waitcnt vmcnt(0) lgkmcnt(0)
	s_barrier
.LBB0_257:
	s_bitcmp1_b32 s76, 0
	s_cselect_b32 s24, 0x6000, 0
	v_add_u32_e32 v46, s24, v37
	v_lshl_add_u64 v[42:43], v[32:33], 0, s[100:101]
	v_readfirstlane_b32 s24, v46
	s_nop 0
	s_mov_b32 m0, s24
	s_mov_b64 s[24:25], 0x204000
	v_lshl_add_u64 v[44:45], v[42:43], 0, s[24:25]
	s_mov_b64 s[24:25], 0x205000
	v_add_u32_e32 v47, 0x1000, v46
	global_load_lds_dwordx4 v[44:45], off
	v_lshl_add_u64 v[44:45], v[42:43], 0, s[24:25]
	v_readfirstlane_b32 s24, v47
	s_mov_b32 m0, s24
	s_mov_b64 s[24:25], 0x206000
	v_add_u32_e32 v47, 0x2000, v46
	global_load_lds_dwordx4 v[44:45], off
	v_lshl_add_u64 v[44:45], v[42:43], 0, s[24:25]
	v_readfirstlane_b32 s24, v47
	s_mov_b32 m0, s24
	s_mov_b64 s[24:25], 0x207000
	global_load_lds_dwordx4 v[44:45], off
	v_add_u32_e32 v44, 0x3000, v46
	v_lshl_add_u64 v[42:43], v[42:43], 0, s[24:25]
	v_readfirstlane_b32 s24, v44
	s_mov_b32 m0, s24
	s_mov_b64 s[24:25], 0x10282000
	global_load_lds_dwordx4 v[42:43], off
	v_lshl_add_u64 v[42:43], v[34:35], 0, s[0:1]
	v_add_u32_e32 v47, 0x4000, v46
	v_lshl_add_u64 v[44:45], v[42:43], 0, s[24:25]
	v_readfirstlane_b32 s24, v47
	s_mov_b32 m0, s24
	s_mov_b64 s[24:25], 0x10283000
	global_load_lds_dwordx4 v[44:45], off
	v_add_u32_e32 v44, 0x5000, v46
	v_lshl_add_u64 v[42:43], v[42:43], 0, s[24:25]
	v_readfirstlane_b32 s24, v44
	s_mov_b32 m0, s24
	s_nop 0
	global_load_lds_dwordx4 v[42:43], off
	s_cselect_b32 s24, 0, 0x6000
	v_or_b32_e32 v42, s24, v40
	v_add3_u32 v42, v42, v39, v38
	v_add_u32_e32 v43, s24, v41
	v_add3_u32 v74, v43, v39, v38
	ds_read_b128 v[42:45], v42 offset:16384
	ds_read_b128 v[46:49], v74
	ds_read_b128 v[50:53], v74 offset:1024
	ds_read_b128 v[54:57], v74 offset:2048
	ds_read_b128 v[58:61], v74 offset:3072
	ds_read_b128 v[62:65], v74 offset:4096
	ds_read_b128 v[66:69], v74 offset:5120
	ds_read_b128 v[70:73], v74 offset:6144
	ds_read_b128 v[74:77], v74 offset:7168
	s_setprio 1
	s_waitcnt lgkmcnt(0)
	v_mfma_f32_16x16x32_bf16 v[28:31], v[42:45], v[46:49], v[28:31]
	v_mfma_f32_16x16x32_bf16 v[24:27], v[42:45], v[50:53], v[24:27]
	v_mfma_f32_16x16x32_bf16 v[20:23], v[42:45], v[54:57], v[20:23]
	v_mfma_f32_16x16x32_bf16 v[16:19], v[42:45], v[58:61], v[16:19]
	v_mfma_f32_16x16x32_bf16 v[12:15], v[42:45], v[62:65], v[12:15]
	v_mfma_f32_16x16x32_bf16 v[8:11], v[42:45], v[66:69], v[8:11]
	v_mfma_f32_16x16x32_bf16 v[4:7], v[42:45], v[70:73], v[4:7]
	v_mfma_f32_16x16x32_bf16 v[0:3], v[42:45], v[74:77], v[0:3]
	s_setprio 0
	s_add_u32 s0, s0, 0x42000
	s_addc_u32 s1, s1, 0
	s_add_u32 s100, s100, 0x204000
	s_addc_u32 s101, s101, 0
	s_add_i32 s76, s76, 1
	s_cmp_eq_u32 s0, 0x7fe000
	s_waitcnt vmcnt(0)
	s_barrier
	s_cbranch_scc0 .LBB0_257
	v_add3_u32 v32, v40, v39, v38
	v_add3_u32 v37, v41, v39, v38
	ds_read_b128 v[32:35], v32 offset:40960
	ds_read_b128 v[38:41], v37 offset:24576
	ds_read_b128 v[42:45], v37 offset:25600
	ds_read_b128 v[46:49], v37 offset:26624
	ds_read_b128 v[50:53], v37 offset:27648
	ds_read_b128 v[54:57], v37 offset:28672
	ds_read_b128 v[58:61], v37 offset:29696
	ds_read_b128 v[62:65], v37 offset:30720
	ds_read_b128 v[66:69], v37 offset:31744
	s_setprio 1
	s_waitcnt lgkmcnt(7)
	v_mfma_f32_16x16x32_bf16 v[28:31], v[32:35], v[38:41], v[28:31]
	s_waitcnt lgkmcnt(6)
	v_mfma_f32_16x16x32_bf16 v[24:27], v[32:35], v[42:45], v[24:27]
	s_waitcnt lgkmcnt(5)
	v_mfma_f32_16x16x32_bf16 v[20:23], v[32:35], v[46:49], v[20:23]
	s_waitcnt lgkmcnt(4)
	v_mfma_f32_16x16x32_bf16 v[16:19], v[32:35], v[50:53], v[16:19]
	s_waitcnt lgkmcnt(3)
	v_mfma_f32_16x16x32_bf16 v[12:15], v[32:35], v[54:57], v[12:15]
	s_waitcnt lgkmcnt(2)
	v_mfma_f32_16x16x32_bf16 v[8:11], v[32:35], v[58:61], v[8:11]
	s_waitcnt lgkmcnt(1)
	v_mfma_f32_16x16x32_bf16 v[4:7], v[32:35], v[62:65], v[4:7]
	s_waitcnt lgkmcnt(0)
	v_mfma_f32_16x16x32_bf16 v[0:3], v[32:35], v[66:69], v[0:3]
	s_setprio 0
	v_and_b32_e32 v32, 64, v36
	v_cmp_eq_u32_e32 vcc, 0, v32
	s_barrier
	s_and_saveexec_b64 s[0:1], vcc
	s_cbranch_execz .LBB0_260
	v_and_b32_e32 v32, 0xffffff80, v36
	v_add_u32_e32 v32, s33, v32
	v_and_or_b32 v32, v36, 15, v32
	v_and_b32_e32 v128, 48, v36
	v_ashrrev_i32_e32 v33, 31, v32
	v_lshl_add_u64 v[34:35], s[6:7], 0, v[128:129]
	v_lshlrev_b64 v[36:37], 6, v[32:33]
	v_lshl_add_u64 v[36:37], v[34:35], 0, v[36:37]
	global_store_dwordx4 v[36:37], v[28:31], off
	s_nop 1
	v_or_b32_e32 v28, 16, v32
	v_ashrrev_i32_e32 v29, 31, v28
	v_lshlrev_b64 v[28:29], 6, v[28:29]
	v_lshl_add_u64 v[28:29], v[34:35], 0, v[28:29]
	global_store_dwordx4 v[28:29], v[24:27], off
	s_nop 1
	v_or_b32_e32 v24, 32, v32
	v_ashrrev_i32_e32 v25, 31, v24
	v_lshlrev_b64 v[24:25], 6, v[24:25]
	v_lshl_add_u64 v[24:25], v[34:35], 0, v[24:25]
	global_store_dwordx4 v[24:25], v[20:23], off
	s_nop 1
	v_or_b32_e32 v20, 48, v32
	v_ashrrev_i32_e32 v21, 31, v20
	v_lshlrev_b64 v[20:21], 6, v[20:21]
	v_lshl_add_u64 v[20:21], v[34:35], 0, v[20:21]
	global_store_dwordx4 v[20:21], v[16:19], off
	s_nop 1
	v_or_b32_e32 v16, 64, v32
	v_ashrrev_i32_e32 v17, 31, v16
	v_lshlrev_b64 v[16:17], 6, v[16:17]
	v_lshl_add_u64 v[16:17], v[34:35], 0, v[16:17]
	global_store_dwordx4 v[16:17], v[12:15], off
	s_nop 1
	v_or_b32_e32 v12, 0x50, v32
	v_ashrrev_i32_e32 v13, 31, v12
	v_lshlrev_b64 v[12:13], 6, v[12:13]
	v_lshl_add_u64 v[12:13], v[34:35], 0, v[12:13]
	global_store_dwordx4 v[12:13], v[8:11], off
	s_nop 1
	v_or_b32_e32 v8, 0x60, v32
	v_ashrrev_i32_e32 v9, 31, v8
	v_lshlrev_b64 v[8:9], 6, v[8:9]
	v_lshl_add_u64 v[8:9], v[34:35], 0, v[8:9]
	global_store_dwordx4 v[8:9], v[4:7], off
	s_nop 1
	v_or_b32_e32 v4, 0x70, v32
	v_ashrrev_i32_e32 v5, 31, v4
	v_lshlrev_b64 v[4:5], 6, v[4:5]
	v_lshl_add_u64 v[4:5], v[34:35], 0, v[4:5]
	global_store_dwordx4 v[4:5], v[0:3], off

.LBB0_261:
	s_and_b64 vcc, exec, s[0:1]
	s_cbranch_vccz .LBB0_254
	v_mov_b32_e32 v141, v181
	v_mov_b32_e32 v10, v181
	s_lshl_b32 s76, s96, 7
	s_waitcnt vmcnt(0)
	v_ashrrev_i32_e32 v0, 2, v10
	v_ashrrev_i32_e32 v1, 31, v0
	v_add_u32_e32 v8, s76, v0
	v_lshlrev_b64 v[2:3], 6, v[0:1]
	v_lshlrev_b32_e32 v1, 3, v10
	v_ashrrev_i32_e32 v9, 31, v8
	v_bitop3_b32 v6, v1, 24, v10 bitop3:0x48
	v_lshlrev_b64 v[8:9], 6, v[8:9]
	v_lshl_add_u64 v[4:5], s[50:51], 0, v[2:3]
	v_lshlrev_b32_e32 v128, 1, v6
	v_lshl_add_u64 v[8:9], s[4:5], 0, v[8:9]
	v_lshl_add_u64 v[4:5], v[4:5], 0, v[128:129]
	v_lshl_add_u64 v[8:9], v[8:9], 0, v[128:129]
	v_lshlrev_b32_e32 v128, 4, v10
	v_add_u32_e32 v12, 0x1000, v128
	v_readfirstlane_b32 s0, v128
	v_lshl_add_u64 v[6:7], v[4:5], 0, s[10:11]
	s_mov_b32 m0, s0
	v_readfirstlane_b32 s0, v12
	v_add_u32_e32 v12, 0x2000, v128
	s_barrier
	global_load_lds_dwordx4 v[6:7], off
	v_lshl_add_u64 v[6:7], v[4:5], 0, s[12:13]
	s_mov_b32 m0, s0
	v_readfirstlane_b32 s0, v12
	global_load_lds_dwordx4 v[6:7], off
	v_lshl_add_u64 v[6:7], v[4:5], 0, s[14:15]
	s_mov_b32 m0, s0
	v_lshl_add_u64 v[4:5], v[4:5], 0, s[16:17]
	global_load_lds_dwordx4 v[6:7], off
	v_add_u32_e32 v6, 0x3000, v128
	v_xor_b32_e32 v11, v1, v10
	v_readfirstlane_b32 s0, v6
	s_mov_b32 m0, s0
	v_add_u32_e32 v6, 0x5000, v128
	global_load_lds_dwordx4 v[4:5], off
	v_add_u32_e32 v4, 0x4000, v128
	v_bitop3_b32 v134, v1, 48, v10 bitop3:0x48
	v_readfirstlane_b32 s0, v4
	s_mov_b32 m0, s0
	v_readfirstlane_b32 s0, v6
	global_load_lds_dwordx4 v[8:9], off
	v_lshl_add_u64 v[4:5], v[8:9], 0, s[8:9]
	s_mov_b32 m0, s0
	v_lshlrev_b32_e32 v1, 6, v10
	global_load_lds_dwordx4 v[4:5], off
	v_and_b32_e32 v137, 0x1000, v1
	v_and_b32_e32 v135, 0x3c0, v1
	v_and_b32_e32 v136, 0xffffe000, v1
	v_lshlrev_b32_e32 v1, 1, v11
	v_add_u32_e32 v0, s85, v0
	v_and_b32_e32 v4, 48, v1
	v_ashrrev_i32_e32 v1, 31, v0
	v_lshlrev_b64 v[0:1], 6, v[0:1]
	v_or_b32_e32 v0, v0, v4
	v_or_b32_e32 v2, v2, v4
	v_lshl_add_u64 v[132:133], s[20:21], 0, v[0:1]
	v_mov_b32_e32 v0, 0
	s_mov_b32 s77, 1
	v_lshl_add_u64 v[130:131], s[50:51], 0, v[2:3]
	s_mov_b64 s[0:1], 0
	s_mov_b64 s[100:101], 0
	v_mov_b32_e32 v1, v0
	v_mov_b32_e32 v2, v0
	v_mov_b32_e32 v3, v0
	v_mov_b32_e32 v4, v0
	v_mov_b32_e32 v5, v0
	v_mov_b32_e32 v6, v0
	v_mov_b32_e32 v7, v0
	v_mov_b32_e32 v8, v0
	v_mov_b32_e32 v9, v0
	v_mov_b32_e32 v10, v0
	v_mov_b32_e32 v11, v0
	v_mov_b32_e32 v12, v0
	v_mov_b32_e32 v13, v0
	v_mov_b32_e32 v14, v0
	v_mov_b32_e32 v15, v0
	v_mov_b32_e32 v16, v0
	v_mov_b32_e32 v17, v0
	v_mov_b32_e32 v18, v0
	v_mov_b32_e32 v19, v0
	v_mov_b32_e32 v20, v0
	v_mov_b32_e32 v21, v0
	v_mov_b32_e32 v22, v0
	v_mov_b32_e32 v23, v0
	v_mov_b32_e32 v24, v0
	v_mov_b32_e32 v25, v0
	v_mov_b32_e32 v26, v0
	v_mov_b32_e32 v27, v0
	v_mov_b32_e32 v28, v0
	v_mov_b32_e32 v29, v0
	v_mov_b32_e32 v30, v0
	v_mov_b32_e32 v31, v0
	v_mov_b32_e32 v32, v0
	v_mov_b32_e32 v33, v0
	v_mov_b32_e32 v34, v0
	v_mov_b32_e32 v35, v0
	v_mov_b32_e32 v36, v0
	v_mov_b32_e32 v37, v0
	v_mov_b32_e32 v38, v0
	v_mov_b32_e32 v39, v0
	v_mov_b32_e32 v40, v0
	v_mov_b32_e32 v41, v0
	v_mov_b32_e32 v42, v0
	v_mov_b32_e32 v43, v0
	v_mov_b32_e32 v44, v0
	v_mov_b32_e32 v45, v0
	v_mov_b32_e32 v46, v0
	v_mov_b32_e32 v47, v0
	v_mov_b32_e32 v48, v0
	v_mov_b32_e32 v49, v0
	v_mov_b32_e32 v50, v0
	v_mov_b32_e32 v51, v0
	v_mov_b32_e32 v52, v0
	v_mov_b32_e32 v53, v0
	v_mov_b32_e32 v54, v0
	v_mov_b32_e32 v55, v0
	v_mov_b32_e32 v56, v0
	v_mov_b32_e32 v57, v0
	v_mov_b32_e32 v58, v0
	v_mov_b32_e32 v59, v0
	v_mov_b32_e32 v64, v0
	v_mov_b32_e32 v65, v0
	v_mov_b32_e32 v66, v0
	v_mov_b32_e32 v67, v0
	v_mov_b32_e32 v60, v0
	v_mov_b32_e32 v61, v0
	v_mov_b32_e32 v62, v0
	v_mov_b32_e32 v63, v0
	v_mov_b32_e32 v68, v0
	v_mov_b32_e32 v69, v0
	v_mov_b32_e32 v70, v0
	v_mov_b32_e32 v71, v0
	v_mov_b32_e32 v72, v0
	v_mov_b32_e32 v73, v0
	v_mov_b32_e32 v74, v0
	v_mov_b32_e32 v75, v0
	v_mov_b32_e32 v76, v0
	v_mov_b32_e32 v77, v0
	v_mov_b32_e32 v78, v0
	v_mov_b32_e32 v79, v0
	v_mov_b32_e32 v80, v0
	v_mov_b32_e32 v81, v0
	v_mov_b32_e32 v82, v0
	v_mov_b32_e32 v83, v0
	v_mov_b32_e32 v84, v0
	v_mov_b32_e32 v85, v0
	v_mov_b32_e32 v86, v0
	v_mov_b32_e32 v87, v0
	v_mov_b32_e32 v88, v0
	v_mov_b32_e32 v89, v0
	v_mov_b32_e32 v90, v0
	v_mov_b32_e32 v91, v0
	v_mov_b32_e32 v92, v0
	v_mov_b32_e32 v93, v0
	v_mov_b32_e32 v94, v0
	v_mov_b32_e32 v95, v0
	v_mov_b32_e32 v96, v0
	v_mov_b32_e32 v97, v0
	v_mov_b32_e32 v98, v0
	v_mov_b32_e32 v99, v0
	v_mov_b32_e32 v100, v0
	v_mov_b32_e32 v101, v0
	v_mov_b32_e32 v102, v0
	v_mov_b32_e32 v103, v0
	v_mov_b32_e32 v104, v0
	v_mov_b32_e32 v105, v0
	v_mov_b32_e32 v106, v0
	v_mov_b32_e32 v107, v0
	v_mov_b32_e32 v108, v0
	v_mov_b32_e32 v109, v0
	v_mov_b32_e32 v110, v0
	v_mov_b32_e32 v111, v0
	v_mov_b32_e32 v112, v0
	v_mov_b32_e32 v113, v0
	v_mov_b32_e32 v114, v0
	v_mov_b32_e32 v115, v0
	v_mov_b32_e32 v116, v0
	v_mov_b32_e32 v117, v0
	v_mov_b32_e32 v118, v0
	v_mov_b32_e32 v119, v0
	v_mov_b32_e32 v120, v0
	v_mov_b32_e32 v121, v0
	v_mov_b32_e32 v122, v0
	v_mov_b32_e32 v123, v0
	v_mov_b32_e32 v124, v0
	v_mov_b32_e32 v125, v0
	v_mov_b32_e32 v126, v0
	v_mov_b32_e32 v127, v0
	s_waitcnt vmcnt(0) lgkmcnt(0)
	s_barrier
.LBB0_263:
	s_bitcmp1_b32 s77, 0
	s_cselect_b32 s24, 0x6000, 0
	v_add_u32_e32 v144, s24, v128
	v_lshl_add_u64 v[138:139], v[130:131], 0, s[100:101]
	v_readfirstlane_b32 s24, v144
	v_add_u32_e32 v145, 0x1000, v144
	v_lshl_add_u64 v[142:143], v[138:139], 0, s[34:35]
	s_mov_b32 m0, s24
	v_readfirstlane_b32 s24, v145
	v_add_u32_e32 v145, 0x2000, v144
	global_load_lds_dwordx4 v[142:143], off
	v_lshl_add_u64 v[142:143], v[138:139], 0, s[46:47]
	s_mov_b32 m0, s24
	v_readfirstlane_b32 s24, v145
	global_load_lds_dwordx4 v[142:143], off
	v_lshl_add_u64 v[142:143], v[138:139], 0, s[62:63]
	s_mov_b32 m0, s24
	v_lshl_add_u64 v[138:139], v[138:139], 0, s[64:65]
	global_load_lds_dwordx4 v[142:143], off
	v_add_u32_e32 v142, 0x3000, v144
	v_add_u32_e32 v145, 0x4000, v144
	v_readfirstlane_b32 s24, v142
	s_mov_b32 m0, s24
	v_readfirstlane_b32 s24, v145
	global_load_lds_dwordx4 v[138:139], off
	v_lshl_add_u64 v[138:139], v[132:133], 0, s[0:1]
	v_lshl_add_u64 v[142:143], v[138:139], 0, s[68:69]
	s_mov_b32 m0, s24
	v_lshl_add_u64 v[138:139], v[138:139], 0, s[70:71]
	global_load_lds_dwordx4 v[142:143], off
	v_add_u32_e32 v142, 0x5000, v144
	s_nop 0
	v_readfirstlane_b32 s24, v142
	s_mov_b32 m0, s24
	s_nop 0
	global_load_lds_dwordx4 v[138:139], off
	s_cselect_b32 s24, 0, 0x6000
	v_or_b32_e32 v138, s24, v137
	v_add3_u32 v138, v138, v135, v134
	ds_read_b128 v[142:145], v138 offset:16384
	ds_read_b128 v[146:149], v138 offset:17408
	ds_read_b128 v[150:153], v138 offset:18432
	ds_read_b128 v[154:157], v138 offset:19456
	v_add_u32_e32 v138, s24, v136
	v_add3_u32 v138, v138, v135, v134
	ds_read_b128 v[158:161], v138
	ds_read_b128 v[162:165], v138 offset:1024
	ds_read_b128 v[166:169], v138 offset:2048
	ds_read_b128 v[170:173], v138 offset:3072
	ds_read_b128 v[174:177], v138 offset:4096
	ds_read_b128 v[184:187], v138 offset:5120
	ds_read_b128 v[188:191], v138 offset:6144
	ds_read_b128 v[192:195], v138 offset:7168
	s_setprio 1
	s_waitcnt lgkmcnt(0)
	v_mfma_f32_16x16x32_bf16 v[124:127], v[142:145], v[158:161], v[124:127]
	v_mfma_f32_16x16x32_bf16 v[120:123], v[146:149], v[158:161], v[120:123]
	v_mfma_f32_16x16x32_bf16 v[116:119], v[150:153], v[158:161], v[116:119]
	v_mfma_f32_16x16x32_bf16 v[112:115], v[154:157], v[158:161], v[112:115]
	v_mfma_f32_16x16x32_bf16 v[108:111], v[142:145], v[162:165], v[108:111]
	v_mfma_f32_16x16x32_bf16 v[104:107], v[146:149], v[162:165], v[104:107]
	v_mfma_f32_16x16x32_bf16 v[100:103], v[150:153], v[162:165], v[100:103]
	v_mfma_f32_16x16x32_bf16 v[96:99], v[154:157], v[162:165], v[96:99]
	v_mfma_f32_16x16x32_bf16 v[92:95], v[142:145], v[166:169], v[92:95]
	v_mfma_f32_16x16x32_bf16 v[88:91], v[146:149], v[166:169], v[88:91]
	v_mfma_f32_16x16x32_bf16 v[84:87], v[150:153], v[166:169], v[84:87]
	v_mfma_f32_16x16x32_bf16 v[80:83], v[154:157], v[166:169], v[80:83]
	v_mfma_f32_16x16x32_bf16 v[76:79], v[142:145], v[170:173], v[76:79]
	v_mfma_f32_16x16x32_bf16 v[72:75], v[146:149], v[170:173], v[72:75]
	v_mfma_f32_16x16x32_bf16 v[68:71], v[150:153], v[170:173], v[68:71]
	v_mfma_f32_16x16x32_bf16 v[60:63], v[154:157], v[170:173], v[60:63]
	v_mfma_f32_16x16x32_bf16 v[64:67], v[142:145], v[174:177], v[64:67]
	v_mfma_f32_16x16x32_bf16 v[56:59], v[146:149], v[174:177], v[56:59]
	v_mfma_f32_16x16x32_bf16 v[52:55], v[150:153], v[174:177], v[52:55]
	v_mfma_f32_16x16x32_bf16 v[48:51], v[154:157], v[174:177], v[48:51]
	v_mfma_f32_16x16x32_bf16 v[44:47], v[142:145], v[184:187], v[44:47]
	v_mfma_f32_16x16x32_bf16 v[40:43], v[146:149], v[184:187], v[40:43]
	v_mfma_f32_16x16x32_bf16 v[36:39], v[150:153], v[184:187], v[36:39]
	v_mfma_f32_16x16x32_bf16 v[32:35], v[154:157], v[184:187], v[32:35]
	v_mfma_f32_16x16x32_bf16 v[28:31], v[142:145], v[188:191], v[28:31]
	v_mfma_f32_16x16x32_bf16 v[24:27], v[146:149], v[188:191], v[24:27]
	v_mfma_f32_16x16x32_bf16 v[20:23], v[150:153], v[188:191], v[20:23]
	v_mfma_f32_16x16x32_bf16 v[16:19], v[154:157], v[188:191], v[16:19]
	v_mfma_f32_16x16x32_bf16 v[12:15], v[142:145], v[192:195], v[12:15]
	v_mfma_f32_16x16x32_bf16 v[8:11], v[146:149], v[192:195], v[8:11]
	v_mfma_f32_16x16x32_bf16 v[4:7], v[150:153], v[192:195], v[4:7]
	v_mfma_f32_16x16x32_bf16 v[0:3], v[154:157], v[192:195], v[0:3]
	s_setprio 0
	s_add_u32 s0, s0, 0x42000
	s_addc_u32 s1, s1, 0
	s_add_u32 s100, s100, 0x204000
	s_addc_u32 s101, s101, 0
	s_add_i32 s77, s77, 1
	s_cmp_eq_u32 s0, 0x7fe000
	s_waitcnt vmcnt(0)
	s_barrier
	s_cbranch_scc0 .LBB0_263
	v_bfe_u32 v144, v141, 6, 1
	v_and_b32_e32 v143, 15, v141
	v_bfe_u32 v145, v141, 4, 2
	v_add3_u32 v128, v137, v135, v134
	ds_read_b128 v[130:133], v128 offset:40960
	ds_read_b128 v[146:149], v128 offset:41984
	ds_read_b128 v[150:153], v128 offset:43008
	ds_read_b128 v[154:157], v128 offset:44032
	v_add3_u32 v128, v136, v135, v134
	ds_read_b128 v[134:137], v128 offset:24576
	ds_read_b128 v[158:161], v128 offset:25600
	ds_read_b128 v[162:165], v128 offset:26624
	ds_read_b128 v[166:169], v128 offset:27648
	ds_read_b128 v[170:173], v128 offset:28672
	ds_read_b128 v[174:177], v128 offset:29696
	ds_read_b128 v[184:187], v128 offset:30720
	ds_read_b128 v[188:191], v128 offset:31744
	s_setprio 1
	s_waitcnt lgkmcnt(7)
	v_mfma_f32_16x16x32_bf16 v[124:127], v[130:133], v[134:137], v[124:127]
	v_mfma_f32_16x16x32_bf16 v[120:123], v[146:149], v[134:137], v[120:123]
	v_mfma_f32_16x16x32_bf16 v[116:119], v[150:153], v[134:137], v[116:119]
	v_mfma_f32_16x16x32_bf16 v[112:115], v[154:157], v[134:137], v[112:115]
	s_waitcnt lgkmcnt(6)
	v_mfma_f32_16x16x32_bf16 v[108:111], v[130:133], v[158:161], v[108:111]
	v_mfma_f32_16x16x32_bf16 v[104:107], v[146:149], v[158:161], v[104:107]
	v_mfma_f32_16x16x32_bf16 v[100:103], v[150:153], v[158:161], v[100:103]
	v_mfma_f32_16x16x32_bf16 v[96:99], v[154:157], v[158:161], v[96:99]
	s_waitcnt lgkmcnt(5)
	v_mfma_f32_16x16x32_bf16 v[92:95], v[130:133], v[162:165], v[92:95]
	v_mfma_f32_16x16x32_bf16 v[88:91], v[146:149], v[162:165], v[88:91]
	v_mfma_f32_16x16x32_bf16 v[84:87], v[150:153], v[162:165], v[84:87]
	v_mfma_f32_16x16x32_bf16 v[80:83], v[154:157], v[162:165], v[80:83]
	s_waitcnt lgkmcnt(4)
	v_mfma_f32_16x16x32_bf16 v[76:79], v[130:133], v[166:169], v[76:79]
	v_mfma_f32_16x16x32_bf16 v[72:75], v[146:149], v[166:169], v[72:75]
	v_mfma_f32_16x16x32_bf16 v[68:71], v[150:153], v[166:169], v[68:71]
	v_mfma_f32_16x16x32_bf16 v[60:63], v[154:157], v[166:169], v[60:63]
	s_waitcnt lgkmcnt(3)
	v_mfma_f32_16x16x32_bf16 v[64:67], v[130:133], v[170:173], v[64:67]
	v_mfma_f32_16x16x32_bf16 v[56:59], v[146:149], v[170:173], v[56:59]
	v_mfma_f32_16x16x32_bf16 v[52:55], v[150:153], v[170:173], v[52:55]
	v_mfma_f32_16x16x32_bf16 v[48:51], v[154:157], v[170:173], v[48:51]
	s_waitcnt lgkmcnt(2)
	v_mfma_f32_16x16x32_bf16 v[44:47], v[130:133], v[174:177], v[44:47]
	v_mfma_f32_16x16x32_bf16 v[40:43], v[146:149], v[174:177], v[40:43]
	v_mfma_f32_16x16x32_bf16 v[36:39], v[150:153], v[174:177], v[36:39]
	v_mfma_f32_16x16x32_bf16 v[32:35], v[154:157], v[174:177], v[32:35]
	s_waitcnt lgkmcnt(1)
	v_mfma_f32_16x16x32_bf16 v[28:31], v[130:133], v[184:187], v[28:31]
	v_mfma_f32_16x16x32_bf16 v[24:27], v[146:149], v[184:187], v[24:27]
	v_mfma_f32_16x16x32_bf16 v[20:23], v[150:153], v[184:187], v[20:23]
	v_mfma_f32_16x16x32_bf16 v[16:19], v[154:157], v[184:187], v[16:19]
	s_waitcnt lgkmcnt(0)
	v_mfma_f32_16x16x32_bf16 v[12:15], v[130:133], v[188:191], v[12:15]
	v_mfma_f32_16x16x32_bf16 v[8:11], v[146:149], v[188:191], v[8:11]
	v_mfma_f32_16x16x32_bf16 v[4:7], v[150:153], v[188:191], v[4:7]
	v_mfma_f32_16x16x32_bf16 v[0:3], v[154:157], v[188:191], v[0:3]
	s_setprio 0
	s_cmp_lt_i32 s96, 12
	v_and_b32_e32 v142, 0xffffff80, v141
	s_barrier
	s_cbranch_scc0 .LBB0_364
	v_lshlrev_b32_e32 v128, 6, v144
	v_lshlrev_b32_e32 v130, 2, v145
	v_lshrrev_b32_e32 v131, 4, v142
	v_add_u32_e32 v147, 0x8000, v142
	v_or3_b32 v130, v128, v130, s76
	v_subrev_co_u32_e32 v128, vcc, 13, v143
	v_lshl_add_u32 v148, v131, 1, v131
	v_or_b32_e32 v146, v147, v143
	v_add_u32_e32 v131, v148, v128
	v_mov_b64_e32 v[132:133], s[50:51]
	s_xor_b64 s[78:79], vcc, -1
	v_cmp_lt_i32_e32 vcc, s87, v146
	v_mad_u64_u32 v[132:133], s[0:1], v131, s90, v[132:133]
	v_lshl_add_u64 v[138:139], v[132:133], 0, s[72:73]
	s_and_b64 s[0:1], vcc, s[78:79]
	v_ashrrev_i32_e32 v131, 31, v130
	s_and_saveexec_b64 s[80:81], s[0:1]
	s_cbranch_execnz .LBB0_368
	s_or_b64 exec, exec, s[80:81]
	s_and_saveexec_b64 s[80:81], s[0:1]
	s_cbranch_execnz .LBB0_369
